# v27 + halo rows stored write-through (sc1) by the tiles that hold them; the projection->mixers seam skips the full L2 write-back when the group sits on one XCC
# speedup vs baseline: 1.0080x; 1.0080x over previous
.LBB0_186:
	v_add_co_u32_e32 v14, vcc, 0x1e4000, v140
	v_cvt_pk_bf16_f32 v10, v10, v11
	v_cvt_pk_bf16_f32 v11, v20, v21
	v_cvt_pk_bf16_f32 v12, v12, v13
	v_cvt_pk_bf16_f32 v13, v16, v17
	s_nop 1
	v_addc_co_u32_e32 v15, vcc, 0, v141, vcc
	s_lshr_b32 s98, s94, 12
	s_and_b32 s98, s98, 7
	s_cmp_eq_u32 s98, 7
	s_cselect_b32 s98, 1, 0
	s_cmp_gt_i32 s30, 9
	s_cselect_b32 s99, 1, 0
	s_and_b32 s98, s98, s99
	s_cbranch_scc0 .Lhw_plain0
	global_store_dwordx4 v[14:15], v[10:13], off sc1
	s_branch .Lhw_done0
.Lhw_plain0:
	global_store_dwordx4 v[14:15], v[10:13], off
.Lhw_done0:
	v_mov_b32_e32 v14, 0
	s_and_b64 vcc, exec, s[0:1]
	v_mov_b32_e32 v15, 0
	s_cbranch_vccnz .LBB0_188
	v_lshlrev_b32_e32 v15, 16, v10
	v_and_b32_e32 v10, 0xffff0000, v10
	v_add_f32_e32 v14, v15, v10
	v_mul_f32_e32 v17, v10, v10
	v_lshlrev_b32_e32 v10, 16, v11
	v_and_b32_e32 v20, 0xffff0000, v11
	v_mul_f32_e32 v15, v15, v15
	v_mul_f32_e32 v11, v10, v10
	v_mul_f32_e32 v21, v20, v20
	v_lshlrev_b32_e32 v22, 16, v12
	v_and_b32_e32 v24, 0xffff0000, v12
	v_mov_b32_e32 v16, v27
	v_mul_f32_e32 v23, v22, v22
	v_mul_f32_e32 v25, v24, v24
	v_lshlrev_b32_e32 v12, 16, v13
	v_and_b32_e32 v28, 0xffff0000, v13
	v_pk_add_f32 v[14:15], v[14:15], v[16:17]
	v_pk_add_f32 v[10:11], v[10:11], v[20:21]
	v_mul_f32_e32 v13, v12, v12
	v_mul_f32_e32 v29, v28, v28
	v_pk_add_f32 v[10:11], v[14:15], v[10:11]
	v_pk_add_f32 v[14:15], v[22:23], v[24:25]
	v_pk_add_f32 v[12:13], v[12:13], v[28:29]
	v_pk_add_f32 v[10:11], v[10:11], v[14:15]
	s_nop 0
	v_pk_add_f32 v[14:15], v[10:11], v[12:13]

.LBB0_190:
	v_cvt_pk_bf16_f32 v2, v2, v3
	v_cvt_pk_bf16_f32 v3, v4, v5
	v_cvt_pk_bf16_f32 v4, v6, v7
	v_add_co_u32_e32 v6, vcc, 0x1e4000, v140
	v_cvt_pk_bf16_f32 v5, v8, v9
	s_nop 1
	v_addc_co_u32_e32 v7, vcc, 0, v141, vcc
	s_and_b64 vcc, exec, s[0:1]
	s_cmp_lg_u32 s98, 0
	s_cbranch_scc0 .Lhw_plain1
	global_store_dwordx4 v[6:7], v[2:5], off offset:256 sc1
	s_branch .Lhw_done1
.Lhw_plain1:
	global_store_dwordx4 v[6:7], v[2:5], off offset:256
.Lhw_done1:
	s_cbranch_vccnz .LBB0_194
	v_lshlrev_b32_e32 v6, 16, v2
	v_and_b32_e32 v8, 0xffff0000, v2
	v_mul_f32_e32 v7, v6, v6
	v_mul_f32_e32 v9, v8, v8
	v_lshlrev_b32_e32 v2, 16, v3
	v_and_b32_e32 v10, 0xffff0000, v3
	v_mul_f32_e32 v3, v2, v2
	v_mul_f32_e32 v11, v10, v10
	v_lshlrev_b32_e32 v12, 16, v4
	v_and_b32_e32 v16, 0xffff0000, v4
	v_pk_add_f32 v[6:7], v[6:7], v[8:9]
	v_mul_f32_e32 v13, v12, v12
	v_mul_f32_e32 v17, v16, v16
	v_lshlrev_b32_e32 v4, 16, v5
	v_and_b32_e32 v18, 0xffff0000, v5
	v_pk_add_f32 v[6:7], v[14:15], v[6:7]
	v_pk_add_f32 v[2:3], v[2:3], v[10:11]
	v_mul_f32_e32 v5, v4, v4
	v_mul_f32_e32 v19, v18, v18
	v_pk_add_f32 v[2:3], v[6:7], v[2:3]
	v_pk_add_f32 v[6:7], v[12:13], v[16:17]
	v_pk_add_f32 v[4:5], v[4:5], v[18:19]
	v_pk_add_f32 v[2:3], v[2:3], v[6:7]
	s_nop 0
	v_pk_add_f32 v[2:3], v[2:3], v[4:5]
	ds_bpermute_b32 v4, v189, v2
	ds_bpermute_b32 v5, v189, v3
	s_waitcnt lgkmcnt(0)
	v_pk_add_f32 v[2:3], v[2:3], v[4:5]
	ds_bpermute_b32 v4, v190, v2
	ds_bpermute_b32 v5, v190, v3
	s_and_saveexec_b64 s[0:1], s[38:39]
	s_cbranch_execz .LBB0_193
	s_lshl_b64 s[72:73], s[94:95], 2
	s_add_u32 s12, s62, s72
	s_addc_u32 s72, s63, s73
	s_lshl_b32 s30, s30, 3
	s_add_i32 s30, s30, s26
	s_ashr_i32 s31, s30, 31
	s_lshl_b64 s[30:31], s[30:31], 2
	s_add_u32 s30, s12, s30
	s_addc_u32 s31, s72, s31
	s_waitcnt lgkmcnt(0)
	v_pk_add_f32 v[2:3], v[2:3], v[4:5]
	v_lshl_add_u64 v[4:5], s[30:31], 0, v[26:27]
	v_add_co_u32_e32 v4, vcc, 0x2000, v4
	s_nop 1
	v_addc_co_u32_e32 v5, vcc, 0, v5, vcc
	global_store_dwordx2 v[4:5], v[2:3], off offset:3072

.LBB0_234:
	s_or_b64 exec, exec, s[20:21]
	v_cvt_f32_u32_e32 v6, v4
	s_waitcnt vmcnt(0)
	v_readfirstlane_b32 s11, v5
	v_sub_u32_e32 v5, 0, v4
	v_rcp_iflag_f32_e32 v6, v6
	v_add_u32_e32 v3, s11, v3
	v_mul_f32_e32 v6, 0x4f7ffffe, v6
	v_cvt_u32_f32_e32 v6, v6
	v_mul_lo_u32 v5, v5, v6
	v_mul_hi_u32 v5, v6, v5
	v_add_u32_e32 v5, v6, v5
	v_mul_hi_u32 v5, v3, v5
	v_mul_lo_u32 v6, v5, v4
	v_sub_u32_e32 v6, v3, v6
	v_add_u32_e32 v7, 1, v5
	v_cmp_ge_u32_e32 vcc, v6, v4
	s_nop 1
	v_cndmask_b32_e32 v5, v5, v7, vcc
	v_sub_u32_e32 v7, v6, v4
	v_cndmask_b32_e32 v6, v6, v7, vcc
	v_add_u32_e32 v7, 1, v5
	v_cmp_ge_u32_e32 vcc, v6, v4
	v_add_u32_e32 v6, 1, v3
	s_nop 0
	v_cndmask_b32_e32 v5, v5, v7, vcc
	v_add_u32_e32 v3, 1, v5
	v_mul_lo_u32 v4, v3, v4
	v_cmp_eq_u32_e32 vcc, v6, v4
	s_and_saveexec_b64 s[20:21], vcc
	s_cbranch_execz .LBB0_237
	s_mov_b64 s[28:29], exec
	v_mbcnt_lo_u32_b32 v4, s28, 0
	v_cmp_ne_u32_e32 vcc, 1, v2
	s_cbranch_vccz .Lhalo_nowb
	buffer_wbl2 sc1
.Lhalo_nowb:
	s_waitcnt lgkmcnt(0)
	s_waitcnt vmcnt(0)
	v_mbcnt_hi_u32_b32 v4, s29, v4
	v_cmp_eq_u32_e32 vcc, 0, v4
	s_and_b64 s[16:17], exec, vcc
	s_mov_b64 exec, s[16:17]
	s_cbranch_execz .LBB0_237
	s_bcnt1_i32_b64 s11, s[28:29]
	v_readlane_b32 s4, v253, 39
	v_mov_b32_e32 v4, s11
	v_readlane_b32 s5, v253, 40
	s_nop 4
	global_atomic_add v27, v4, s[4:5]
